# P1 rotary epilogue: 16 serialized cos/sin loads (each behind vmcnt(0)) replaced by one batched prefetch + counted waits
# baseline (speedup 1.0000x reference)
; __device__ __forceinline__ unsigned cvt_pk_bf16(float lo, float hi) { f32x2_t v = {lo, hi}; bf16x2_t b = __builtin_convertvector(v, bf16x2_t); return __builtin_bit_cast(unsigned, b); }
;     __device__ __forceinline__ void operator()(const f32x4 (&acc)[2][2][4][2], const Unit& u, int wr, int wc, int fr, int fq) const {
;     ...
;             const float sc = (kind == 0) ? qscale : 1.0f;
;             const int j = 4 * (wc & 1) + fq;
;             const int lc0 = (pc0 & ~63) + 4 * j;
; #pragma unroll
;             for (int ai = 0; ai < 2; ++ai)
; #pragma unroll
;                 for (int m = 0; m < 4; ++m) { const int row = row0 + ai * HALF + m * 16; const int pos = row & 4095;
;                     const f32x4 cs = *(const f32x4*)(cosT + pos * 32 + 4 * j) * sc, sn = *(const f32x4*)(sinT + pos * 32 + 4 * j) * sc;
;                     bf16_t* rowp = base + (size_t)row * 512 + lc0;
; #pragma unroll
;                     for (int bj = 0; bj < 2; ++bj) { const f32x4 x1 = acc[ai][bj][m][0], x2 = acc[ai][bj][m][1];
;                         const f32x4 o1 = x1 * cs - x2 * sn, o2 = x2 * cs + x1 * sn;
;                         u32x2 w1, w2; w1.x = cvt_pk_bf16(o1[0], o1[1]); w1.y = cvt_pk_bf16(o1[2], o1[3]); w2.x = cvt_pk_bf16(o2[0], o2[1]); w2.y = cvt_pk_bf16(o2[2], o2[3]);
;                         *(u32x2*)(rowp + bj * HALF) = w1; *(u32x2*)(rowp + bj * HALF + 32) = w2; } }
.LBB0_141:
	s_and_b32 s10, s11, 0x140
	v_or_b32_e32 v146, s10, v157
	v_lshlrev_b32_e32 v188, 1, v146
	v_lshlrev_b32_e32 v159, 7, v144
	v_lshl_add_u64 v[146:147], s[54:55], 0, v[188:189]
	v_lshlrev_b32_e32 v188, 7, v144
	v_and_b32_e32 v188, 0x7ff80, v188
	v_lshl_add_u64 v[174:175], v[136:137], 0, v[188:189]
	global_load_dwordx4 v[160:163], v[174:175], off
	v_lshl_add_u64 v[174:175], v[138:139], 0, v[188:189]
	global_load_dwordx4 v[170:173], v[174:175], off
	v_add_u32_e32 v188, 16, v144
	v_lshlrev_b32_e32 v188, 7, v188
	v_and_b32_e32 v188, 0x7ff80, v188
	v_lshl_add_u64 v[174:175], v[136:137], 0, v[188:189]
	global_load_dwordx4 v[176:179], v[174:175], off
	v_lshl_add_u64 v[174:175], v[138:139], 0, v[188:189]
	global_load_dwordx4 v[180:183], v[174:175], off
	v_add_u32_e32 v188, 32, v144
	v_lshlrev_b32_e32 v188, 7, v188
	v_and_b32_e32 v188, 0x7ff80, v188
	v_lshl_add_u64 v[174:175], v[136:137], 0, v[188:189]
	global_load_dwordx4 v[198:201], v[174:175], off
	v_lshl_add_u64 v[174:175], v[138:139], 0, v[188:189]
	global_load_dwordx4 v[202:205], v[174:175], off
	v_add_u32_e32 v188, 48, v144
	v_lshlrev_b32_e32 v188, 7, v188
	v_and_b32_e32 v188, 0x7ff80, v188
	v_lshl_add_u64 v[174:175], v[136:137], 0, v[188:189]
	global_load_dwordx4 v[206:209], v[174:175], off
	v_lshl_add_u64 v[174:175], v[138:139], 0, v[188:189]
	global_load_dwordx4 v[210:213], v[174:175], off
	v_add_u32_e32 v188, 0x80, v144
	v_lshlrev_b32_e32 v188, 7, v188
	v_and_b32_e32 v188, 0x7ff80, v188
	v_lshl_add_u64 v[174:175], v[136:137], 0, v[188:189]
	global_load_dwordx4 v[214:217], v[174:175], off
	v_lshl_add_u64 v[174:175], v[138:139], 0, v[188:189]
	global_load_dwordx4 v[226:229], v[174:175], off
	v_add_u32_e32 v188, 0x90, v144
	v_lshlrev_b32_e32 v188, 7, v188
	v_and_b32_e32 v188, 0x7ff80, v188
	v_lshl_add_u64 v[174:175], v[136:137], 0, v[188:189]
	global_load_dwordx4 v[230:233], v[174:175], off
	v_lshl_add_u64 v[174:175], v[138:139], 0, v[188:189]
	global_load_dwordx4 v[234:237], v[174:175], off
	v_add_u32_e32 v188, 0xa0, v144
	v_lshlrev_b32_e32 v188, 7, v188
	v_and_b32_e32 v188, 0x7ff80, v188
	v_lshl_add_u64 v[174:175], v[136:137], 0, v[188:189]
	global_load_dwordx4 v[238:241], v[174:175], off
	v_lshl_add_u64 v[174:175], v[138:139], 0, v[188:189]
	global_load_dwordx4 v[242:245], v[174:175], off
	v_add_u32_e32 v188, 0xb0, v144
	v_lshlrev_b32_e32 v188, 7, v188
	v_and_b32_e32 v188, 0x7ff80, v188
	v_lshl_add_u64 v[174:175], v[136:137], 0, v[188:189]
	global_load_dwordx4 v[246:249], v[174:175], off
	v_lshl_add_u64 v[174:175], v[138:139], 0, v[188:189]
	global_load_dwordx4 v[250:253], v[174:175], off
	v_and_b32_e32 v188, 0x7e780, v159
	v_lshlrev_b64 v[168:169], 10, v[144:145]
	v_lshl_add_u64 v[168:169], v[146:147], 0, v[168:169]
	s_waitcnt vmcnt(14)
	v_pk_mul_f32 v[164:165], v[160:161], s[24:25] op_sel_hi:[1,0]
	v_lshl_add_u64 v[160:161], v[138:139], 0, v[188:189]
	v_pk_mul_f32 v[166:167], v[162:163], s[24:25] op_sel_hi:[1,0]
	v_mov_b64_e32 v[160:161], v[170:171]
	v_mov_b64_e32 v[162:163], v[172:173]
	v_pk_mul_f32 v[162:163], s[24:25], v[162:163] op_sel_hi:[0,1]
	v_pk_mul_f32 v[160:161], s[24:25], v[160:161] op_sel_hi:[0,1]
	v_pk_mul_f32 v[170:171], v[120:121], v[160:161]
	v_pk_mul_f32 v[172:173], v[122:123], v[162:163]
	v_pk_mul_f32 v[120:121], v[120:121], v[164:165]
	v_pk_mul_f32 v[122:123], v[122:123], v[166:167]
	v_pk_fma_f32 v[172:173], v[126:127], v[166:167], v[172:173] neg_lo:[0,0,1] neg_hi:[0,0,1]
	v_pk_fma_f32 v[170:171], v[124:125], v[164:165], v[170:171] neg_lo:[0,0,1] neg_hi:[0,0,1]
	v_pk_fma_f32 v[122:123], v[126:127], v[162:163], v[122:123]
	v_pk_fma_f32 v[120:121], v[124:125], v[160:161], v[120:121]
	v_cvt_pk_bf16_f32 v124, v170, v171
	v_cvt_pk_bf16_f32 v125, v172, v173
	v_cvt_pk_bf16_f32 v120, v120, v121
	v_cvt_pk_bf16_f32 v121, v122, v123
	global_store_dwordx2 v[168:169], v[124:125], off
	global_store_dwordx2 v[168:169], v[120:121], off offset:64
	v_pk_mul_f32 v[120:121], v[112:113], v[160:161]
	v_pk_mul_f32 v[122:123], v[114:115], v[162:163]
	v_pk_mul_f32 v[112:113], v[112:113], v[164:165]
	v_pk_fma_f32 v[122:123], v[118:119], v[166:167], v[122:123] neg_lo:[0,0,1] neg_hi:[0,0,1]
	v_pk_fma_f32 v[120:121], v[116:117], v[164:165], v[120:121] neg_lo:[0,0,1] neg_hi:[0,0,1]
	v_pk_mul_f32 v[114:115], v[114:115], v[166:167]
	v_pk_fma_f32 v[112:113], v[116:117], v[160:161], v[112:113]
	v_pk_fma_f32 v[114:115], v[118:119], v[162:163], v[114:115]
	v_cvt_pk_bf16_f32 v116, v120, v121
	v_cvt_pk_bf16_f32 v117, v122, v123
	v_cvt_pk_bf16_f32 v112, v112, v113
	v_cvt_pk_bf16_f32 v113, v114, v115
	global_store_dwordx2 v[168:169], v[116:117], off offset:256
	global_store_dwordx2 v[168:169], v[112:113], off offset:320
	v_lshlrev_b32_e32 v112, 7, v152
	v_and_b32_e32 v188, 0x7ef80, v112
	v_lshl_add_u64 v[112:113], v[136:137], 0, v[188:189]
	s_waitcnt vmcnt(16)
; __device__ __forceinline__ unsigned cvt_pk_bf16(float lo, float hi) { f32x2_t v = {lo, hi}; bf16x2_t b = __builtin_convertvector(v, bf16x2_t); return __builtin_bit_cast(unsigned, b); }
;     __device__ __forceinline__ void operator()(const f32x4 (&acc)[2][2][4][2], const Unit& u, int wr, int wc, int fr, int fq) const {
;     ...
;                 for (int m = 0; m < 4; ++m) { const int row = row0 + ai * HALF + m * 16; const int pos = row & 4095;
;                     const f32x4 cs = *(const f32x4*)(cosT + pos * 32 + 4 * j) * sc, sn = *(const f32x4*)(sinT + pos * 32 + 4 * j) * sc;
;                     bf16_t* rowp = base + (size_t)row * 512 + lc0;
; #pragma unroll
;                     for (int bj = 0; bj < 2; ++bj) { const f32x4 x1 = acc[ai][bj][m][0], x2 = acc[ai][bj][m][1];
;                         const f32x4 o1 = x1 * cs - x2 * sn, o2 = x2 * cs + x1 * sn;
;                         u32x2 w1, w2; w1.x = cvt_pk_bf16(o1[0], o1[1]); w1.y = cvt_pk_bf16(o1[2], o1[3]); w2.x = cvt_pk_bf16(o2[0], o2[1]); w2.y = cvt_pk_bf16(o2[2], o2[3]);
;                         *(u32x2*)(rowp + bj * HALF) = w1; *(u32x2*)(rowp + bj * HALF + 32) = w2; } }
	v_mov_b64_e32 v[112:113], v[176:177]
	v_mov_b64_e32 v[114:115], v[178:179]
	v_lshlrev_b64 v[120:121], 10, v[152:153]
	v_lshl_add_u64 v[120:121], v[146:147], 0, v[120:121]
	v_pk_mul_f32 v[116:117], s[24:25], v[112:113] op_sel_hi:[0,1]
	v_lshl_add_u64 v[112:113], v[138:139], 0, v[188:189]
	v_pk_mul_f32 v[118:119], s[24:25], v[114:115] op_sel_hi:[0,1]
	v_mov_b64_e32 v[112:113], v[180:181]
	v_mov_b64_e32 v[114:115], v[182:183]
	v_pk_mul_f32 v[114:115], s[24:25], v[114:115] op_sel_hi:[0,1]
	v_pk_mul_f32 v[112:113], s[24:25], v[112:113] op_sel_hi:[0,1]
	v_pk_mul_f32 v[122:123], v[104:105], v[112:113]
	v_pk_mul_f32 v[124:125], v[106:107], v[114:115]
	v_pk_fma_f32 v[122:123], v[108:109], v[116:117], v[122:123] neg_lo:[0,0,1] neg_hi:[0,0,1]
	v_pk_fma_f32 v[124:125], v[110:111], v[118:119], v[124:125] neg_lo:[0,0,1] neg_hi:[0,0,1]
	v_pk_mul_f32 v[108:109], v[108:109], v[112:113]
	v_pk_mul_f32 v[110:111], v[110:111], v[114:115]
	v_pk_fma_f32 v[104:105], v[104:105], v[116:117], v[108:109]
	v_pk_fma_f32 v[106:107], v[106:107], v[118:119], v[110:111]
	v_cvt_pk_bf16_f32 v108, v122, v123
	v_cvt_pk_bf16_f32 v109, v124, v125
	v_cvt_pk_bf16_f32 v104, v104, v105
	v_cvt_pk_bf16_f32 v105, v106, v107
	global_store_dwordx2 v[120:121], v[108:109], off
	global_store_dwordx2 v[120:121], v[104:105], off offset:64
	v_pk_mul_f32 v[104:105], v[96:97], v[112:113]
	v_pk_mul_f32 v[106:107], v[98:99], v[114:115]
	v_pk_fma_f32 v[104:105], v[100:101], v[116:117], v[104:105] neg_lo:[0,0,1] neg_hi:[0,0,1]
	v_pk_mul_f32 v[100:101], v[100:101], v[112:113]
	v_pk_fma_f32 v[106:107], v[102:103], v[118:119], v[106:107] neg_lo:[0,0,1] neg_hi:[0,0,1]
	v_pk_mul_f32 v[102:103], v[102:103], v[114:115]
	v_pk_fma_f32 v[96:97], v[96:97], v[116:117], v[100:101]
	v_pk_fma_f32 v[98:99], v[98:99], v[118:119], v[102:103]
	v_cvt_pk_bf16_f32 v100, v104, v105
	v_cvt_pk_bf16_f32 v101, v106, v107
	v_cvt_pk_bf16_f32 v96, v96, v97
	v_cvt_pk_bf16_f32 v97, v98, v99
	global_store_dwordx2 v[120:121], v[100:101], off offset:256
	global_store_dwordx2 v[120:121], v[96:97], off offset:320
	v_lshlrev_b32_e32 v96, 7, v150
	v_and_b32_e32 v188, 0x7f780, v96
	v_lshl_add_u64 v[96:97], v[136:137], 0, v[188:189]
	s_waitcnt vmcnt(18)
	v_mov_b64_e32 v[96:97], v[198:199]
	v_mov_b64_e32 v[98:99], v[200:201]
	v_lshlrev_b64 v[104:105], 10, v[150:151]
	v_lshl_add_u64 v[104:105], v[146:147], 0, v[104:105]
	v_pk_mul_f32 v[100:101], s[24:25], v[96:97] op_sel_hi:[0,1]
	v_lshl_add_u64 v[96:97], v[138:139], 0, v[188:189]
	v_pk_mul_f32 v[102:103], s[24:25], v[98:99] op_sel_hi:[0,1]
	v_mov_b64_e32 v[96:97], v[202:203]
	v_mov_b64_e32 v[98:99], v[204:205]
	v_pk_mul_f32 v[98:99], s[24:25], v[98:99] op_sel_hi:[0,1]
	v_pk_mul_f32 v[96:97], s[24:25], v[96:97] op_sel_hi:[0,1]
	v_pk_mul_f32 v[106:107], v[88:89], v[96:97]
	v_pk_mul_f32 v[108:109], v[90:91], v[98:99]
	v_pk_fma_f32 v[106:107], v[92:93], v[100:101], v[106:107] neg_lo:[0,0,1] neg_hi:[0,0,1]
	v_pk_fma_f32 v[108:109], v[94:95], v[102:103], v[108:109] neg_lo:[0,0,1] neg_hi:[0,0,1]
	v_pk_mul_f32 v[92:93], v[92:93], v[96:97]
	v_pk_mul_f32 v[94:95], v[94:95], v[98:99]
	v_pk_fma_f32 v[88:89], v[88:89], v[100:101], v[92:93]
	v_pk_fma_f32 v[90:91], v[90:91], v[102:103], v[94:95]
	v_cvt_pk_bf16_f32 v92, v106, v107
	v_cvt_pk_bf16_f32 v93, v108, v109
	v_cvt_pk_bf16_f32 v88, v88, v89
	v_cvt_pk_bf16_f32 v89, v90, v91
	global_store_dwordx2 v[104:105], v[92:93], off
	global_store_dwordx2 v[104:105], v[88:89], off offset:64
	v_pk_mul_f32 v[88:89], v[80:81], v[96:97]
	v_pk_mul_f32 v[90:91], v[82:83], v[98:99]
	v_pk_fma_f32 v[88:89], v[84:85], v[100:101], v[88:89] neg_lo:[0,0,1] neg_hi:[0,0,1]
	v_pk_mul_f32 v[84:85], v[84:85], v[96:97]
	v_pk_fma_f32 v[90:91], v[86:87], v[102:103], v[90:91] neg_lo:[0,0,1] neg_hi:[0,0,1]
	v_pk_mul_f32 v[86:87], v[86:87], v[98:99]
	v_pk_fma_f32 v[80:81], v[80:81], v[100:101], v[84:85]
	v_pk_fma_f32 v[82:83], v[82:83], v[102:103], v[86:87]
	v_cvt_pk_bf16_f32 v84, v88, v89
	v_cvt_pk_bf16_f32 v85, v90, v91
	v_cvt_pk_bf16_f32 v80, v80, v81
	v_cvt_pk_bf16_f32 v81, v82, v83
	global_store_dwordx2 v[104:105], v[84:85], off offset:256
	global_store_dwordx2 v[104:105], v[80:81], off offset:320
	v_lshlrev_b32_e32 v80, 7, v148
	v_and_b32_e32 v188, 0x7ff80, v80
	v_lshl_add_u64 v[80:81], v[136:137], 0, v[188:189]
	s_waitcnt vmcnt(20)
	v_mov_b64_e32 v[80:81], v[206:207]
	v_mov_b64_e32 v[82:83], v[208:209]
	v_lshlrev_b64 v[88:89], 10, v[148:149]
	v_lshl_add_u64 v[88:89], v[146:147], 0, v[88:89]
	v_pk_mul_f32 v[84:85], s[24:25], v[80:81] op_sel_hi:[0,1]
	v_lshl_add_u64 v[80:81], v[138:139], 0, v[188:189]
	v_pk_mul_f32 v[86:87], s[24:25], v[82:83] op_sel_hi:[0,1]
	v_mov_b64_e32 v[80:81], v[210:211]
	v_mov_b64_e32 v[82:83], v[212:213]
	v_pk_mul_f32 v[82:83], s[24:25], v[82:83] op_sel_hi:[0,1]
	v_pk_mul_f32 v[80:81], s[24:25], v[80:81] op_sel_hi:[0,1]
	v_pk_mul_f32 v[90:91], v[72:73], v[80:81]
	v_pk_mul_f32 v[92:93], v[74:75], v[82:83]
	v_pk_fma_f32 v[90:91], v[76:77], v[84:85], v[90:91] neg_lo:[0,0,1] neg_hi:[0,0,1]
	v_pk_fma_f32 v[92:93], v[78:79], v[86:87], v[92:93] neg_lo:[0,0,1] neg_hi:[0,0,1]
	v_pk_mul_f32 v[76:77], v[76:77], v[80:81]
	v_pk_mul_f32 v[78:79], v[78:79], v[82:83]
	v_pk_fma_f32 v[72:73], v[72:73], v[84:85], v[76:77]
	v_pk_fma_f32 v[74:75], v[74:75], v[86:87], v[78:79]
	v_cvt_pk_bf16_f32 v76, v90, v91
	v_cvt_pk_bf16_f32 v77, v92, v93
	v_cvt_pk_bf16_f32 v72, v72, v73
	v_cvt_pk_bf16_f32 v73, v74, v75
	global_store_dwordx2 v[88:89], v[76:77], off
	global_store_dwordx2 v[88:89], v[72:73], off offset:64
	v_pk_mul_f32 v[72:73], v[64:65], v[80:81]
	v_pk_mul_f32 v[74:75], v[66:67], v[82:83]
	v_pk_fma_f32 v[72:73], v[68:69], v[84:85], v[72:73] neg_lo:[0,0,1] neg_hi:[0,0,1]
	v_pk_fma_f32 v[74:75], v[70:71], v[86:87], v[74:75] neg_lo:[0,0,1] neg_hi:[0,0,1]
	v_pk_mul_f32 v[68:69], v[68:69], v[80:81]
	v_pk_mul_f32 v[70:71], v[70:71], v[82:83]
	v_pk_fma_f32 v[64:65], v[64:65], v[84:85], v[68:69]
	v_pk_fma_f32 v[66:67], v[66:67], v[86:87], v[70:71]
	v_cvt_pk_bf16_f32 v68, v72, v73
	v_cvt_pk_bf16_f32 v69, v74, v75
	v_cvt_pk_bf16_f32 v64, v64, v65
	v_cvt_pk_bf16_f32 v65, v66, v67
	global_store_dwordx2 v[88:89], v[68:69], off offset:256
	global_store_dwordx2 v[88:89], v[64:65], off offset:320
	v_add_u32_e32 v68, 0x80, v144
	v_lshlrev_b32_e32 v64, 7, v68
	v_and_b32_e32 v188, 0x7e780, v64
	v_lshl_add_u64 v[64:65], v[136:137], 0, v[188:189]
	s_waitcnt vmcnt(22)
; __device__ __forceinline__ unsigned cvt_pk_bf16(float lo, float hi) { f32x2_t v = {lo, hi}; bf16x2_t b = __builtin_convertvector(v, bf16x2_t); return __builtin_bit_cast(unsigned, b); }
;     __device__ __forceinline__ void operator()(const f32x4 (&acc)[2][2][4][2], const Unit& u, int wr, int wc, int fr, int fq) const {
;     ...
;                 for (int m = 0; m < 4; ++m) { const int row = row0 + ai * HALF + m * 16; const int pos = row & 4095;
;                     const f32x4 cs = *(const f32x4*)(cosT + pos * 32 + 4 * j) * sc, sn = *(const f32x4*)(sinT + pos * 32 + 4 * j) * sc;
;                     bf16_t* rowp = base + (size_t)row * 512 + lc0;
; #pragma unroll
;                     for (int bj = 0; bj < 2; ++bj) { const f32x4 x1 = acc[ai][bj][m][0], x2 = acc[ai][bj][m][1];
;                         const f32x4 o1 = x1 * cs - x2 * sn, o2 = x2 * cs + x1 * sn;
;                         u32x2 w1, w2; w1.x = cvt_pk_bf16(o1[0], o1[1]); w1.y = cvt_pk_bf16(o1[2], o1[3]); w2.x = cvt_pk_bf16(o2[0], o2[1]); w2.y = cvt_pk_bf16(o2[2], o2[3]);
;                         *(u32x2*)(rowp + bj * HALF) = w1; *(u32x2*)(rowp + bj * HALF + 32) = w2; } }
	v_mov_b64_e32 v[64:65], v[214:215]
	v_mov_b64_e32 v[66:67], v[216:217]
	v_ashrrev_i32_e32 v69, 31, v68
	v_lshlrev_b64 v[68:69], 10, v[68:69]
	v_lshl_add_u64 v[68:69], v[146:147], 0, v[68:69]
	v_pk_mul_f32 v[70:71], s[24:25], v[64:65] op_sel_hi:[0,1]
	v_lshl_add_u64 v[64:65], v[138:139], 0, v[188:189]
	v_pk_mul_f32 v[72:73], s[24:25], v[66:67] op_sel_hi:[0,1]
	v_mov_b64_e32 v[64:65], v[226:227]
	v_mov_b64_e32 v[66:67], v[228:229]
	v_pk_mul_f32 v[66:67], s[24:25], v[66:67] op_sel_hi:[0,1]
	v_pk_mul_f32 v[64:65], s[24:25], v[64:65] op_sel_hi:[0,1]
	v_pk_mul_f32 v[74:75], v[56:57], v[64:65]
	v_pk_mul_f32 v[76:77], v[58:59], v[66:67]
	v_pk_fma_f32 v[74:75], v[60:61], v[70:71], v[74:75] neg_lo:[0,0,1] neg_hi:[0,0,1]
	v_pk_fma_f32 v[76:77], v[62:63], v[72:73], v[76:77] neg_lo:[0,0,1] neg_hi:[0,0,1]
	v_pk_mul_f32 v[60:61], v[60:61], v[64:65]
	v_pk_mul_f32 v[62:63], v[62:63], v[66:67]
	v_pk_fma_f32 v[56:57], v[56:57], v[70:71], v[60:61]
	v_pk_fma_f32 v[58:59], v[58:59], v[72:73], v[62:63]
	v_cvt_pk_bf16_f32 v60, v74, v75
	v_cvt_pk_bf16_f32 v61, v76, v77
	v_cvt_pk_bf16_f32 v56, v56, v57
	v_cvt_pk_bf16_f32 v57, v58, v59
	global_store_dwordx2 v[68:69], v[60:61], off
	global_store_dwordx2 v[68:69], v[56:57], off offset:64
	v_pk_mul_f32 v[56:57], v[48:49], v[64:65]
	v_pk_mul_f32 v[58:59], v[50:51], v[66:67]
	v_pk_fma_f32 v[56:57], v[52:53], v[70:71], v[56:57] neg_lo:[0,0,1] neg_hi:[0,0,1]
	v_pk_fma_f32 v[58:59], v[54:55], v[72:73], v[58:59] neg_lo:[0,0,1] neg_hi:[0,0,1]
	v_pk_mul_f32 v[52:53], v[52:53], v[64:65]
	v_pk_mul_f32 v[54:55], v[54:55], v[66:67]
	v_pk_fma_f32 v[48:49], v[48:49], v[70:71], v[52:53]
	v_pk_fma_f32 v[50:51], v[50:51], v[72:73], v[54:55]
	v_cvt_pk_bf16_f32 v52, v56, v57
	v_cvt_pk_bf16_f32 v53, v58, v59
	v_cvt_pk_bf16_f32 v48, v48, v49
	v_cvt_pk_bf16_f32 v49, v50, v51
	global_store_dwordx2 v[68:69], v[52:53], off offset:256
	global_store_dwordx2 v[68:69], v[48:49], off offset:320
	v_add_u32_e32 v52, 0x90, v144
	v_lshlrev_b32_e32 v48, 7, v52
	v_and_b32_e32 v188, 0x7ef80, v48
	v_lshl_add_u64 v[48:49], v[136:137], 0, v[188:189]
	s_waitcnt vmcnt(24)
	v_mov_b64_e32 v[48:49], v[230:231]
	v_mov_b64_e32 v[50:51], v[232:233]
	v_ashrrev_i32_e32 v53, 31, v52
	v_lshlrev_b64 v[52:53], 10, v[52:53]
	v_lshl_add_u64 v[52:53], v[146:147], 0, v[52:53]
	v_pk_mul_f32 v[54:55], s[24:25], v[48:49] op_sel_hi:[0,1]
	v_lshl_add_u64 v[48:49], v[138:139], 0, v[188:189]
	v_pk_mul_f32 v[56:57], s[24:25], v[50:51] op_sel_hi:[0,1]
	v_mov_b64_e32 v[48:49], v[234:235]
	v_mov_b64_e32 v[50:51], v[236:237]
	v_pk_mul_f32 v[50:51], s[24:25], v[50:51] op_sel_hi:[0,1]
	v_pk_mul_f32 v[48:49], s[24:25], v[48:49] op_sel_hi:[0,1]
	v_pk_mul_f32 v[58:59], v[40:41], v[48:49]
	v_pk_mul_f32 v[60:61], v[42:43], v[50:51]
	v_pk_fma_f32 v[58:59], v[44:45], v[54:55], v[58:59] neg_lo:[0,0,1] neg_hi:[0,0,1]
	v_pk_fma_f32 v[60:61], v[46:47], v[56:57], v[60:61] neg_lo:[0,0,1] neg_hi:[0,0,1]
	v_pk_mul_f32 v[44:45], v[44:45], v[48:49]
	v_pk_mul_f32 v[46:47], v[46:47], v[50:51]
	v_pk_fma_f32 v[40:41], v[40:41], v[54:55], v[44:45]
	v_pk_fma_f32 v[42:43], v[42:43], v[56:57], v[46:47]
	v_cvt_pk_bf16_f32 v44, v58, v59
	v_cvt_pk_bf16_f32 v45, v60, v61
	v_cvt_pk_bf16_f32 v40, v40, v41
	v_cvt_pk_bf16_f32 v41, v42, v43
	global_store_dwordx2 v[52:53], v[44:45], off
	global_store_dwordx2 v[52:53], v[40:41], off offset:64
	v_pk_mul_f32 v[40:41], v[32:33], v[48:49]
	v_pk_mul_f32 v[42:43], v[34:35], v[50:51]
	v_pk_fma_f32 v[40:41], v[36:37], v[54:55], v[40:41] neg_lo:[0,0,1] neg_hi:[0,0,1]
	v_pk_fma_f32 v[42:43], v[38:39], v[56:57], v[42:43] neg_lo:[0,0,1] neg_hi:[0,0,1]
	v_pk_mul_f32 v[36:37], v[36:37], v[48:49]
	v_pk_mul_f32 v[38:39], v[38:39], v[50:51]
	v_pk_fma_f32 v[32:33], v[32:33], v[54:55], v[36:37]
	v_pk_fma_f32 v[34:35], v[34:35], v[56:57], v[38:39]
	v_cvt_pk_bf16_f32 v36, v40, v41
	v_cvt_pk_bf16_f32 v37, v42, v43
	v_cvt_pk_bf16_f32 v32, v32, v33
	v_cvt_pk_bf16_f32 v33, v34, v35
	global_store_dwordx2 v[52:53], v[36:37], off offset:256
	global_store_dwordx2 v[52:53], v[32:33], off offset:320
	v_add_u32_e32 v36, 0xa0, v144
	v_lshlrev_b32_e32 v32, 7, v36
	v_and_b32_e32 v188, 0x7f780, v32
	v_lshl_add_u64 v[32:33], v[136:137], 0, v[188:189]
	s_waitcnt vmcnt(26)
; __device__ __forceinline__ unsigned cvt_pk_bf16(float lo, float hi) { f32x2_t v = {lo, hi}; bf16x2_t b = __builtin_convertvector(v, bf16x2_t); return __builtin_bit_cast(unsigned, b); }
;     __device__ __forceinline__ void operator()(const f32x4 (&acc)[2][2][4][2], const Unit& u, int wr, int wc, int fr, int fq) const {
;     ...
;                 for (int m = 0; m < 4; ++m) { const int row = row0 + ai * HALF + m * 16; const int pos = row & 4095;
;                     const f32x4 cs = *(const f32x4*)(cosT + pos * 32 + 4 * j) * sc, sn = *(const f32x4*)(sinT + pos * 32 + 4 * j) * sc;
;                     bf16_t* rowp = base + (size_t)row * 512 + lc0;
; #pragma unroll
;                     for (int bj = 0; bj < 2; ++bj) { const f32x4 x1 = acc[ai][bj][m][0], x2 = acc[ai][bj][m][1];
;                         const f32x4 o1 = x1 * cs - x2 * sn, o2 = x2 * cs + x1 * sn;
;                         u32x2 w1, w2; w1.x = cvt_pk_bf16(o1[0], o1[1]); w1.y = cvt_pk_bf16(o1[2], o1[3]); w2.x = cvt_pk_bf16(o2[0], o2[1]); w2.y = cvt_pk_bf16(o2[2], o2[3]);
;                         *(u32x2*)(rowp + bj * HALF) = w1; *(u32x2*)(rowp + bj * HALF + 32) = w2; } }
	v_mov_b64_e32 v[32:33], v[238:239]
	v_mov_b64_e32 v[34:35], v[240:241]
	v_ashrrev_i32_e32 v37, 31, v36
	v_lshlrev_b64 v[36:37], 10, v[36:37]
	v_lshl_add_u64 v[36:37], v[146:147], 0, v[36:37]
	v_pk_mul_f32 v[38:39], s[24:25], v[32:33] op_sel_hi:[0,1]
	v_lshl_add_u64 v[32:33], v[138:139], 0, v[188:189]
	v_pk_mul_f32 v[40:41], s[24:25], v[34:35] op_sel_hi:[0,1]
	v_mov_b64_e32 v[32:33], v[242:243]
	v_mov_b64_e32 v[34:35], v[244:245]
	v_pk_mul_f32 v[34:35], s[24:25], v[34:35] op_sel_hi:[0,1]
	v_pk_mul_f32 v[32:33], s[24:25], v[32:33] op_sel_hi:[0,1]
	v_pk_mul_f32 v[42:43], v[24:25], v[32:33]
	v_pk_mul_f32 v[44:45], v[26:27], v[34:35]
	v_pk_fma_f32 v[42:43], v[28:29], v[38:39], v[42:43] neg_lo:[0,0,1] neg_hi:[0,0,1]
	v_pk_fma_f32 v[44:45], v[30:31], v[40:41], v[44:45] neg_lo:[0,0,1] neg_hi:[0,0,1]
	v_pk_mul_f32 v[28:29], v[28:29], v[32:33]
	v_pk_mul_f32 v[30:31], v[30:31], v[34:35]
	v_pk_fma_f32 v[24:25], v[24:25], v[38:39], v[28:29]
	v_pk_fma_f32 v[26:27], v[26:27], v[40:41], v[30:31]
	v_cvt_pk_bf16_f32 v28, v42, v43
	v_cvt_pk_bf16_f32 v29, v44, v45
	v_cvt_pk_bf16_f32 v24, v24, v25
	v_cvt_pk_bf16_f32 v25, v26, v27
	global_store_dwordx2 v[36:37], v[28:29], off
	global_store_dwordx2 v[36:37], v[24:25], off offset:64
	v_pk_mul_f32 v[24:25], v[16:17], v[32:33]
	v_pk_mul_f32 v[26:27], v[18:19], v[34:35]
	v_pk_fma_f32 v[24:25], v[20:21], v[38:39], v[24:25] neg_lo:[0,0,1] neg_hi:[0,0,1]
	v_pk_fma_f32 v[26:27], v[22:23], v[40:41], v[26:27] neg_lo:[0,0,1] neg_hi:[0,0,1]
	v_pk_mul_f32 v[20:21], v[20:21], v[32:33]
	v_pk_mul_f32 v[22:23], v[22:23], v[34:35]
	v_pk_fma_f32 v[16:17], v[16:17], v[38:39], v[20:21]
	v_pk_fma_f32 v[18:19], v[18:19], v[40:41], v[22:23]
	v_cvt_pk_bf16_f32 v20, v24, v25
	v_cvt_pk_bf16_f32 v21, v26, v27
	v_cvt_pk_bf16_f32 v16, v16, v17
	v_cvt_pk_bf16_f32 v17, v18, v19
	global_store_dwordx2 v[36:37], v[20:21], off offset:256
	global_store_dwordx2 v[36:37], v[16:17], off offset:320
	v_add_u32_e32 v20, 0xb0, v144
	v_lshlrev_b32_e32 v16, 7, v20
	v_and_b32_e32 v188, 0x7ff80, v16
	v_lshl_add_u64 v[16:17], v[136:137], 0, v[188:189]
	s_waitcnt vmcnt(28)
	v_mov_b64_e32 v[16:17], v[246:247]
	v_mov_b64_e32 v[18:19], v[248:249]
	v_ashrrev_i32_e32 v21, 31, v20
	v_lshlrev_b64 v[20:21], 10, v[20:21]
	v_lshl_add_u64 v[20:21], v[146:147], 0, v[20:21]
	v_pk_mul_f32 v[22:23], s[24:25], v[16:17] op_sel_hi:[0,1]
	v_lshl_add_u64 v[16:17], v[138:139], 0, v[188:189]
	v_pk_mul_f32 v[24:25], s[24:25], v[18:19] op_sel_hi:[0,1]
	v_mov_b64_e32 v[16:17], v[250:251]
	v_mov_b64_e32 v[18:19], v[252:253]
	v_pk_mul_f32 v[18:19], s[24:25], v[18:19] op_sel_hi:[0,1]
	v_pk_mul_f32 v[16:17], s[24:25], v[16:17] op_sel_hi:[0,1]
	v_pk_mul_f32 v[26:27], v[8:9], v[16:17]
	v_pk_mul_f32 v[28:29], v[10:11], v[18:19]
	v_pk_fma_f32 v[26:27], v[12:13], v[22:23], v[26:27] neg_lo:[0,0,1] neg_hi:[0,0,1]
	v_pk_fma_f32 v[28:29], v[14:15], v[24:25], v[28:29] neg_lo:[0,0,1] neg_hi:[0,0,1]
	v_pk_mul_f32 v[12:13], v[12:13], v[16:17]
	v_pk_mul_f32 v[14:15], v[14:15], v[18:19]
	v_pk_fma_f32 v[8:9], v[8:9], v[22:23], v[12:13]
	v_pk_fma_f32 v[10:11], v[10:11], v[24:25], v[14:15]
	v_cvt_pk_bf16_f32 v12, v26, v27
	v_cvt_pk_bf16_f32 v13, v28, v29
	v_cvt_pk_bf16_f32 v8, v8, v9
	v_cvt_pk_bf16_f32 v9, v10, v11
	global_store_dwordx2 v[20:21], v[12:13], off
	global_store_dwordx2 v[20:21], v[8:9], off offset:64
	v_pk_mul_f32 v[8:9], v[0:1], v[16:17]
	v_pk_mul_f32 v[10:11], v[2:3], v[18:19]
	v_pk_fma_f32 v[8:9], v[4:5], v[22:23], v[8:9] neg_lo:[0,0,1] neg_hi:[0,0,1]
	v_pk_fma_f32 v[10:11], v[6:7], v[24:25], v[10:11] neg_lo:[0,0,1] neg_hi:[0,0,1]
	v_pk_mul_f32 v[4:5], v[4:5], v[16:17]
	v_pk_mul_f32 v[6:7], v[6:7], v[18:19]
	v_pk_fma_f32 v[0:1], v[0:1], v[22:23], v[4:5]
	v_pk_fma_f32 v[2:3], v[2:3], v[24:25], v[6:7]
	v_cvt_pk_bf16_f32 v4, v8, v9
	v_cvt_pk_bf16_f32 v5, v10, v11
	v_cvt_pk_bf16_f32 v0, v0, v1
	v_cvt_pk_bf16_f32 v1, v2, v3
	global_store_dwordx2 v[20:21], v[4:5], off offset:256
	global_store_dwordx2 v[20:21], v[0:1], off offset:320
	s_andn2_b64 vcc, exec, s[38:39]
	s_mov_b64 s[38:39], -1
	s_cbranch_vccnz .LBB0_128
